# GEMM1 tail round overlapped with prep items of rounds 27 and 31 on the 152 workgroups without a 16th tile (counter + release/acquire, prep code re-entered before the grid barrier); prep phase proper 3
# baseline (speedup 1.0000x reference)
; template <class Epi>
; __device__ __forceinline__ void gemm_phase(LAS unsigned char* lds, const Gemm g, const StaticOrder& S, const Epi& E) {
;     ...
;         E(acc, cur, wr, wc, fr, fq);
;         if (!has_next) break;
; #pragma unroll
;         for (int a = 0; a < 2; ++a)
; #pragma unroll
;             for (int b = 0; b < 2; ++b)
; #pragma unroll
;                 for (int m = 0; m < 4; ++m)
; #pragma unroll
;                     for (int n = 0; n < 2; ++n) acc[a][b][m][n] = (f32x4){0.f, 0.f, 0.f, 0.f};
;         cur = nxt; cA = nA; cB = nB; ++ui;
.LBB0_76:
	s_or_b64 exec, exec, s[28:29]
	s_and_b64 vcc, exec, s[10:11]
	s_cbranch_vccnz .LBB0_93
	s_cmp_lg_u32 s46, 15
	s_cbranch_scc1 .LBB0_77
	s_waitcnt vmcnt(0)
	s_barrier
	s_lshr_b32 s7, s34, 6
	s_cmp_lg_u32 s7, 4
	s_cbranch_scc1 .LBB0_77
	buffer_wbl2 sc1
	s_waitcnt vmcnt(0)
	s_mov_b64 s[28:29], exec
	s_mov_b64 exec, 1
	v_mov_b32_e32 v0, 0
	v_mov_b32_e32 v1, 1
	global_atomic_add v0, v1, s[36:37] offset:384
	s_mov_b64 exec, s[28:29]

; #define PG8_WAIT_V(n) asm volatile("s_waitcnt vmcnt(" #n ")" ::: "memory")
; #define PG8_BAR __builtin_amdgcn_s_barrier()
; template <class Epi>
; __device__ __forceinline__ void gemm_phase(LAS unsigned char* lds, const Gemm g, const StaticOrder& S, const Epi& E) {
;     ...
;     PG8_WAIT_V(0);
;     if (wr == 0) PG8_BAR;
;     PG8_BAR;
.LBB0_95:
	v_readlane_b32 s40, v244, 6
	s_barrier
	v_readlane_b32 s41, v244, 7
	s_nop 3
	s_cmp_lt_u32 s40, 0x68
	s_cbranch_scc1 .LBB0_96
	s_cmp_gt_u32 s34, 63
	s_cbranch_scc1 .Lg1_sync
	buffer_wbl2 sc1
	s_waitcnt vmcnt(0)
	s_mov_b64 s[2:3], exec
	s_mov_b64 exec, 1
	v_mov_b32_e32 v0, 0
	v_mov_b32_e32 v1, 1
	global_atomic_add v0, v1, s[36:37] offset:384
	s_mov_b32 s4, 0
.Lg1_poll:
	global_load_dword v2, v0, s[36:37] offset:384 sc1
	s_waitcnt vmcnt(0)
	v_readfirstlane_b32 s5, v2
	s_nop 3
	s_cmp_ge_u32 s5, 0x100
	s_cbranch_scc1 .Lg1_polled
	s_sleep 2
	s_add_i32 s4, s4, 1
	s_cmp_lt_u32 s4, 0x800
	s_cbranch_scc1 .Lg1_poll

; __device__ __forceinline__ void phase_prep(const Params& p, unsigned char* shm) {
;     ...
;     for (int item = blockIdx.x; item < NCH * 16; item += gridDim.x) {
;         int tid = threadIdx.x; asm volatile("" : "+v"(tid));
;         const int lane = tid & 63, wid = __builtin_amdgcn_readfirstlane(tid >> 6), fr = lane & 15, fq = lane >> 4;
;         const int h = item & 15, cidx = item >> 4, row0 = cidx * 64; const size_t chbase = (size_t)item * 4096;
.Lg1_sync:
	s_barrier
	s_mov_b32 s77, 1
	s_and_b32 s4, s40, 15
	s_cmp_lt_u32 s4, 8
	s_cselect_b32 s5, 7, 6
	s_lshr_b32 s32, s40, 4
	s_sub_i32 s32, s32, s5
	s_lshl_b32 s5, s32, 4
	s_add_i32 s40, s4, s5
	s_addk_i32 s40, 0x1b00
	s_branch .Lprep_re

; __device__ __forceinline__ void phase_prep(const Params& p, unsigned char* shm) {
;     ...
;     if ((int)blockIdx.x < NCH * 16) zload(blockIdx.x);
;     for (int item = blockIdx.x; item < NCH * 16; item += gridDim.x) {
.LBB0_149:
	s_or_b64 exec, exec, s[2:3]
	s_mov_b32 s77, 0

; __device__ __forceinline__ void phase_prep(const Params& p, unsigned char* shm) {
;     ...
;     auto zload = [&](int it) {
;         const int rw0 = (it >> 4) * 64;
; #pragma unroll
;         for (int i = 0; i < 6; ++i) { int grow = rw0 - 1 + zrow[i]; grow = grow < 0 ? 0 : grow; zpre[i] = *(const u32x4*)(p.Z + (size_t)grow * LDZ + ZC_S + zcol[i]); }
;     };
;     if ((int)blockIdx.x < NCH * 16) zload(blockIdx.x);
;     for (int item = blockIdx.x; item < NCH * 16; item += gridDim.x) {
;         int tid = threadIdx.x; asm volatile("" : "+v"(tid));
;         const int lane = tid & 63, wid = __builtin_amdgcn_readfirstlane(tid >> 6), fr = lane & 15, fq = lane >> 4;
;         const int h = item & 15, cidx = item >> 4, row0 = cidx * 64; const size_t chbase = (size_t)item * 4096;
;         const int crow = tid >> 3, cseg = (tid & 7) * 8;
;         {
;             const bool first = seq_first(row0);
; #pragma unroll
;             for (int i = 0; i < 6; ++i) {
;                 if (zlds[i] >= 0) {
;                     u32x4 v = zpre[i];
;                     if ((i == 0 || i == 2) && first && zrow[i] == 0) { v = (u32x4){0u, 0u, 0u, 0u};
;                         if (row0 >= MP) { const float* sp = p.st_shift + (size_t)((row0 - MP) >> 6) * NSHIFT + zcol[i]; const f32x4 a = *(const f32x4*)sp, b = *(const f32x4*)(sp + 4);
;                             v = (u32x4){pk_bf16(a[0], a[1]), pk_bf16(a[2], a[3]), pk_bf16(b[0], b[1]), pk_bf16(b[2], b[3])}; } }
;                     *(u32x4*)(shm + zlds[i]) = v; } }
;             const int nitem = item + (int)gridDim.x;
;             zload(nitem < NCH * 16 ? nitem : item);
;         }
;         LDS_BARRIER();
;         {
;             const int j = tid >> 3, p8 = tid & 7;
; #pragma unroll
;             for (int isa = 0; isa < 2; ++isa) {
;                 const int c = isa * 64 + 8 * p8;
;                 const u32x4 cu = *(const u32x4*)(zh + (j + 1) * LZH + c), pu = *(const u32x4*)(zh + j * LZH + c);
;                 const f32x4 m0 = *(const f32x4*)(prm + 512 + c), m1 = *(const f32x4*)(prm + 512 + c + 4);
;                 const unsigned cw[4] = {cu.x, cu.y, cu.z, cu.w}, pw[4] = {pu.x, pu.y, pu.z, pu.w};
;                 float x[8];
; #pragma unroll
;                 for (int e = 0; e < 4; ++e) { const float c0 = bf_lo(cw[e]), c1 = bf_hi(cw[e]), mA = e < 2 ? m0[2 * e] : m1[2 * e - 4], mB = e < 2 ? m0[2 * e + 1] : m1[2 * e - 3];
.LBB0_189:
	s_or_b64 exec, exec, s[18:19]
	s_cmp_eq_u32 s77, 1
	s_cbranch_scc1 .Lprep_nx_early
	s_add_i32 s70, s26, s38
	s_lshr_b32 s18, s70, 8
	s_and_b32 s19, s18, 3
	s_cmp_eq_u32 s19, 3
	s_cselect_b32 s19, 1, 0
	s_cmp_ge_u32 s18, 27
	s_cselect_b32 s20, 1, 0
	s_and_b32 s19, s19, s20
	s_cmp_le_u32 s18, 31
	s_cselect_b32 s20, 1, 0
	s_and_b32 s19, s19, s20
	s_lshl_b32 s19, s19, 8
	s_add_i32 s70, s70, s19
	s_branch .Lprep_nx_done
.Lprep_nx_early:
	s_and_b32 s18, s26, 15
	s_cmp_lt_u32 s18, 8
	s_cselect_b32 s19, 9, 10
	s_add_i32 s32, s32, s19
	s_movk_i32 s70, 0x2200
	s_cmp_ge_u32 s32, 32
	s_cbranch_scc1 .Lprep_nx_done
	s_and_b32 s19, s32, 15
	s_lshl_b32 s19, s19, 4
	s_lshr_b32 s20, s32, 4
	s_lshl_b32 s20, s20, 10
	s_add_i32 s70, s18, s19
	s_add_i32 s70, s70, s20
	s_addk_i32 s70, 0x1b00
.Lprep_nx_done:
	s_cmpk_gt_i32 s70, 0x21ff
	s_cselect_b64 s[42:43], -1, 0
	s_cmpk_lt_i32 s70, 0x2200
	s_cselect_b32 s18, s70, s26
	s_mov_b64 s[20:21], s[88:89]
	s_lshl_b32 s18, s18, 2
	s_andn2_b32 s18, s18, 63
	s_add_i32 s22, s18, -1
	v_add_u32_e32 v0, s22, v123
	v_max_i32_e32 v0, 0, v0
	s_mov_b64 s[18:19], s[90:91]
	s_waitcnt vmcnt(6) lgkmcnt(0)
	v_mov_b64_e32 v[8:9], s[20:21]
	v_mad_u64_u32 v[0:1], s[20:21], v0, s3, v[8:9]
	v_lshlrev_b32_e32 v126, 1, v122
	v_add_u32_e32 v2, s22, v176
	v_lshl_add_u64 v[0:1], v[0:1], 0, v[126:127]
	v_max_i32_e32 v2, 0, v2
	v_add_co_u32_e32 v0, vcc, s49, v0
	v_mad_u64_u32 v[2:3], s[20:21], v2, s3, v[8:9]
	v_mov_b32_e32 v137, v127
	v_addc_co_u32_e32 v1, vcc, 0, v1, vcc
	v_lshl_add_u64 v[2:3], v[2:3], 0, v[136:137]
	v_add_co_u32_e32 v2, vcc, s49, v2
	v_mov_b32_e32 v139, v127
	s_nop 0
	v_addc_co_u32_e32 v3, vcc, 0, v3, vcc
	global_load_dwordx4 v[20:23], v[0:1], off offset:2048
	global_load_dwordx4 v[16:19], v[2:3], off offset:2048
	v_add_u32_e32 v0, s22, v121
	v_max_i32_e32 v0, 0, v0
	v_mad_u64_u32 v[0:1], s[20:21], v0, s3, v[8:9]
	v_add_u32_e32 v2, s22, v175
	v_lshl_add_u64 v[0:1], v[124:125], 1, v[0:1]
	v_max_i32_e32 v2, 0, v2
	v_add_co_u32_e32 v0, vcc, s49, v0
	v_mad_u64_u32 v[2:3], s[20:21], v2, s3, v[8:9]
	v_add_u32_sdwa v10, s22, v157 dst_sel:DWORD dst_unused:UNUSED_PAD src0_sel:DWORD src1_sel:WORD_1
	v_addc_co_u32_e32 v1, vcc, 0, v1, vcc
	v_lshl_add_u64 v[2:3], v[2:3], 0, v[138:139]
	v_max_i32_e32 v10, 0, v10
	v_add_co_u32_e32 v2, vcc, s49, v2
	v_mad_u64_u32 v[10:11], s[20:21], v10, s3, v[8:9]
	v_mov_b32_e32 v141, v127
	v_add_u32_sdwa v12, s22, v174 dst_sel:DWORD dst_unused:UNUSED_PAD src0_sel:DWORD src1_sel:WORD_1
	v_addc_co_u32_e32 v3, vcc, 0, v3, vcc
	v_lshl_add_u64 v[10:11], v[10:11], 0, v[140:141]
	v_max_i32_e32 v12, 0, v12
	v_add_co_u32_e32 v10, vcc, s49, v10
	v_mad_u64_u32 v[8:9], s[20:21], v12, s3, v[8:9]
	v_mov_b32_e32 v143, v127
	v_lshlrev_b32_e32 v188, 3, v187
	v_addc_co_u32_e32 v11, vcc, 0, v11, vcc
	v_lshl_add_u64 v[8:9], v[8:9], 0, v[142:143]
	v_ashrrev_i32_e32 v186, 3, v187
	v_and_b32_e32 v32, 56, v188
	v_add_co_u32_e32 v8, vcc, s49, v8
	v_mul_u32_u24_e32 v24, s48, v186
	s_nop 0
	v_addc_co_u32_e32 v9, vcc, 0, v9, vcc
	v_lshlrev_b32_e32 v144, 1, v32
	global_load_dwordx4 v[4:7], v[0:1], off offset:2048
	s_nop 0
	global_load_dwordx4 v[0:3], v[2:3], off offset:2048
	s_nop 0
	global_load_dwordx4 v[12:15], v[10:11], off offset:2048
	s_nop 0
	global_load_dwordx4 v[8:11], v[8:9], off offset:2048
	s_waitcnt lgkmcnt(0)
	s_barrier
	v_add3_u32 v45, 0, v24, v144
	ds_read_b128 v[24:27], v45 offset:37136
	ds_read_b128 v[28:31], v45 offset:36864
	v_lshlrev_b32_e32 v46, 2, v32
	v_add_u32_e32 v32, 0, v46
	v_add_u32_e32 v47, 0x25000, v32
	ds_read_b128 v[32:35], v47
	ds_read_b128 v[36:39], v47 offset:16
	s_waitcnt lgkmcnt(3)
	v_lshlrev_b32_e32 v40, 16, v24
	v_and_b32_e32 v41, 0xffff0000, v24
	s_waitcnt lgkmcnt(2)
	v_lshlrev_b32_e32 v42, 16, v28
	v_and_b32_e32 v43, 0xffff0000, v28
	v_lshlrev_b32_e32 v24, 16, v25
	v_and_b32_e32 v25, 0xffff0000, v25
	v_lshlrev_b32_e32 v28, 16, v29
	v_and_b32_e32 v29, 0xffff0000, v29
	v_pk_add_f32 v[28:29], v[28:29], v[24:25] neg_lo:[0,1] neg_hi:[0,1]
	v_pk_add_f32 v[42:43], v[42:43], v[40:41] neg_lo:[0,1] neg_hi:[0,1]
	s_waitcnt lgkmcnt(1)
	v_pk_fma_f32 v[24:25], v[34:35], v[28:29], v[24:25]
	v_lshlrev_b32_e32 v28, 16, v26
	v_and_b32_e32 v29, 0xffff0000, v26
	v_lshlrev_b32_e32 v34, 16, v30
	v_and_b32_e32 v35, 0xffff0000, v30
	v_lshlrev_b32_e32 v26, 16, v27
	v_and_b32_e32 v27, 0xffff0000, v27
	v_lshlrev_b32_e32 v30, 16, v31
	v_and_b32_e32 v31, 0xffff0000, v31
	v_pk_add_f32 v[34:35], v[34:35], v[28:29] neg_lo:[0,1] neg_hi:[0,1]
	v_pk_add_f32 v[30:31], v[30:31], v[26:27] neg_lo:[0,1] neg_hi:[0,1]
	v_pk_fma_f32 v[32:33], v[32:33], v[42:43], v[40:41]
	s_waitcnt lgkmcnt(0)
	v_pk_fma_f32 v[28:29], v[36:37], v[34:35], v[28:29]
	v_pk_fma_f32 v[26:27], v[38:39], v[30:31], v[26:27]
	v_pk_mul_f32 v[32:33], v[32:33], s[2:3] op_sel_hi:[1,0]
	v_pk_mul_f32 v[24:25], v[24:25], s[2:3] op_sel_hi:[1,0]
	v_pk_mul_f32 v[28:29], v[28:29], s[2:3] op_sel_hi:[1,0]
	v_pk_mul_f32 v[26:27], v[26:27], s[2:3] op_sel_hi:[1,0]
	v_exp_f32_e32 v32, v32
	v_exp_f32_e32 v33, v33
	v_exp_f32_e32 v24, v24
	v_exp_f32_e32 v25, v25
	v_exp_f32_e32 v28, v28
	v_exp_f32_e32 v29, v29
	v_exp_f32_e32 v26, v26
	v_exp_f32_e32 v27, v27
	v_pk_add_f32 v[32:33], v[32:33], 1.0 op_sel_hi:[1,0]
	v_pk_add_f32 v[24:25], v[24:25], 1.0 op_sel_hi:[1,0]
	v_pk_add_f32 v[28:29], v[28:29], 1.0 op_sel_hi:[1,0]
	v_pk_add_f32 v[26:27], v[26:27], 1.0 op_sel_hi:[1,0]
	v_rcp_f32_e32 v32, v32
	v_rcp_f32_e32 v33, v33
	v_rcp_f32_e32 v24, v24
	v_rcp_f32_e32 v25, v25
	v_rcp_f32_e32 v28, v28
	v_rcp_f32_e32 v29, v29
	v_rcp_f32_e32 v26, v26
	v_rcp_f32_e32 v27, v27
	v_mul_u32_u24_e32 v44, s50, v186
	v_pk_fma_f32 v[30:31], v[32:33], 2.0, 1.0 op_sel_hi:[1,0,0] neg_lo:[1,0,0] neg_hi:[1,0,0]
	v_pk_fma_f32 v[32:33], v[24:25], 2.0, 1.0 op_sel_hi:[1,0,0] neg_lo:[1,0,0] neg_hi:[1,0,0]
	v_pk_fma_f32 v[28:29], v[28:29], 2.0, 1.0 op_sel_hi:[1,0,0] neg_lo:[1,0,0] neg_hi:[1,0,0]
	v_pk_fma_f32 v[34:35], v[26:27], 2.0, 1.0 op_sel_hi:[1,0,0] neg_lo:[1,0,0] neg_hi:[1,0,0]
	v_cvt_pk_bf16_f32 v24, v30, v31
	v_cvt_pk_bf16_f32 v25, v32, v33
	v_cvt_pk_bf16_f32 v26, v28, v29
	v_cvt_pk_bf16_f32 v27, v34, v35
	v_add3_u32 v44, 0, v44, v144
	ds_read_b128 v[28:31], v45 offset:37264
	ds_write_b128 v44, v[24:27]
	ds_read_b128 v[24:27], v45 offset:36992
	ds_read_b128 v[32:35], v47 offset:256
	ds_read_b128 v[36:39], v47 offset:272
	s_and_b32 s22, s26, 15
	s_lshl_b32 s40, s22, 7
	s_waitcnt lgkmcnt(4)
; __device__ __forceinline__ float bf_lo(unsigned u) { return __uint_as_float(u << 16); }
; __device__ __forceinline__ void phase_prep(const Params& p, unsigned char* shm) {
;     ...
;                 if (isa == 0) {
; #pragma unroll
;                     for (int e = 0; e < 4; ++e) { const f32x2 th = tanh2((f32x2){x[2 * e], x[2 * e + 1]}); x[2 * e] = th.x; x[2 * e + 1] = th.y; }
;                 }
;                 *(u32x4*)((isa ? tha : thw) + j * LD + 8 * p8) = (u32x4){pk_bf16(x[0], x[1]), pk_bf16(x[2], x[3]), pk_bf16(x[4], x[5]), pk_bf16(x[6], x[7])};
;             }
;             {
;                 const u32x4 cu = *(const u32x4*)(zs + (j + 1) * LZS + 128 + 8 * p8), pu = *(const u32x4*)(zs + j * LZS + 128 + 8 * p8);
;                 const f32x4 m0 = *(const f32x4*)(prm + 256 + 8 * p8), m1 = *(const f32x4*)(prm + 256 + 8 * p8 + 4);
;                 const unsigned cw[4] = {cu.x, cu.y, cu.z, cu.w}, pw[4] = {pu.x, pu.y, pu.z, pu.w};
;                 float x[8];
; #pragma unroll
;                 for (int e = 0; e < 4; ++e) { const float c0 = bf_lo(cw[e]), c1 = bf_hi(cw[e]), mA = e < 2 ? m0[2 * e] : m1[2 * e - 4], mB = e < 2 ? m0[2 * e + 1] : m1[2 * e - 3];
;                     x[2 * e] = c0 + mA * (bf_lo(pw[e]) - c0); x[2 * e + 1] = c1 + mB * (bf_hi(pw[e]) - c1); }
;                 *(u32x4*)(p.PV + ((size_t)(row0 + j) * 16 + h) * 64 + 8 * p8) = (u32x4){pk_bf16(x[0], x[1]), pk_bf16(x[2], x[3]), pk_bf16(x[4], x[5]), pk_bf16(x[6], x[7])};
;             }
;         }
;         LDS_BARRIER();
;         const int tt = wid & 3, chh = wid >> 2, tk = 16 * tt + fr, row = row0 + tk;
;         f32x4 lw[2], av[2], vm[2], kkv[2], kp[2], rm[2], cs[2]; float nrm = 0.f, rk = 0.f;
;         {
;             f32x4 accd[2], acca[2];
; #pragma unroll
;             for (int n = 0; n < 2; ++n) { accd[n] = (f32x4){0.f, 0.f, 0.f, 0.f}; acca[n] = (f32x4){0.f, 0.f, 0.f, 0.f}; }
; #pragma unroll
;             for (int ks = 0; ks < 2; ++ks) {
;                 const bf16x8 bw = ldfrag(thw, LD, 16 * tt, 32 * ks, fr, fq), ba = ldfrag(tha, LD, 16 * tt, 32 * ks, fr, fq);
; #pragma unroll
;                 for (int n = 0; n < 2; ++n) {
;                     accd[n] = MFMA16(ldfrag(w2P, LD, 32 * chh + 16 * n, 32 * ks, fr, fq), bw, accd[n]);
;                     acca[n] = MFMA16(ldfrag(a2P, LD, 32 * chh + 16 * n, 32 * ks, fr, fq), ba, acca[n]);
;                 }
;             }
	v_lshlrev_b32_e32 v40, 16, v28
	v_and_b32_e32 v41, 0xffff0000, v28
	s_waitcnt lgkmcnt(2)
	v_lshlrev_b32_e32 v42, 16, v24
	v_and_b32_e32 v43, 0xffff0000, v24
	v_lshlrev_b32_e32 v28, 16, v29
	v_and_b32_e32 v29, 0xffff0000, v29
	v_lshlrev_b32_e32 v24, 16, v25
	v_and_b32_e32 v25, 0xffff0000, v25
	v_pk_add_f32 v[24:25], v[24:25], v[28:29] neg_lo:[0,1] neg_hi:[0,1]
	v_pk_add_f32 v[42:43], v[42:43], v[40:41] neg_lo:[0,1] neg_hi:[0,1]
	s_waitcnt lgkmcnt(1)
	v_pk_fma_f32 v[28:29], v[34:35], v[24:25], v[28:29]
	v_lshlrev_b32_e32 v24, 16, v30
	v_and_b32_e32 v25, 0xffff0000, v30
	v_lshlrev_b32_e32 v34, 16, v26
	v_and_b32_e32 v35, 0xffff0000, v26
	v_pk_add_f32 v[34:35], v[34:35], v[24:25] neg_lo:[0,1] neg_hi:[0,1]
	v_lshlrev_b32_e32 v26, 16, v27
	s_waitcnt lgkmcnt(0)
	v_pk_fma_f32 v[34:35], v[36:37], v[34:35], v[24:25]
	v_lshlrev_b32_e32 v24, 16, v31
	v_and_b32_e32 v25, 0xffff0000, v31
	v_and_b32_e32 v27, 0xffff0000, v27
	v_pk_add_f32 v[26:27], v[26:27], v[24:25] neg_lo:[0,1] neg_hi:[0,1]
	v_pk_fma_f32 v[32:33], v[32:33], v[42:43], v[40:41]
	v_pk_fma_f32 v[30:31], v[38:39], v[26:27], v[24:25]
	v_cvt_pk_bf16_f32 v24, v32, v33
	v_cvt_pk_bf16_f32 v25, v28, v29
	v_cvt_pk_bf16_f32 v26, v34, v35
	v_cvt_pk_bf16_f32 v27, v30, v31
	ds_write_b128 v44, v[24:27] offset:9216
	v_mul_u32_u24_e32 v24, s51, v186
	v_add3_u32 v28, 0, v24, v144
	ds_read_b128 v[24:27], v28 offset:55200
	ds_read_b128 v[28:31], v28 offset:54800
	v_add_u32_e32 v36, s52, v46
	ds_read_b128 v[32:35], v36
	ds_read_b128 v[36:39], v36 offset:16
	v_mov_b32_e32 v145, v127
	s_waitcnt lgkmcnt(3)
	v_lshlrev_b32_e32 v40, 16, v24
	v_and_b32_e32 v41, 0xffff0000, v24
	s_waitcnt lgkmcnt(2)
	v_lshlrev_b32_e32 v42, 16, v28
	v_and_b32_e32 v43, 0xffff0000, v28
	v_lshlrev_b32_e32 v24, 16, v25
	v_and_b32_e32 v25, 0xffff0000, v25
	v_lshlrev_b32_e32 v28, 16, v29
	v_and_b32_e32 v29, 0xffff0000, v29
	v_pk_add_f32 v[28:29], v[28:29], v[24:25] neg_lo:[0,1] neg_hi:[0,1]
	v_pk_add_f32 v[42:43], v[42:43], v[40:41] neg_lo:[0,1] neg_hi:[0,1]
	s_waitcnt lgkmcnt(1)
	v_pk_fma_f32 v[28:29], v[34:35], v[28:29], v[24:25]
	v_lshlrev_b32_e32 v24, 16, v26
	v_and_b32_e32 v25, 0xffff0000, v26
	v_lshlrev_b32_e32 v34, 16, v30
	v_and_b32_e32 v35, 0xffff0000, v30
	v_pk_add_f32 v[34:35], v[34:35], v[24:25] neg_lo:[0,1] neg_hi:[0,1]
	v_lshlrev_b32_e32 v26, 16, v31
	s_waitcnt lgkmcnt(0)
	v_pk_fma_f32 v[34:35], v[36:37], v[34:35], v[24:25]
	v_lshlrev_b32_e32 v24, 16, v27
	v_and_b32_e32 v25, 0xffff0000, v27
	v_and_b32_e32 v27, 0xffff0000, v31
	v_pk_add_f32 v[26:27], v[26:27], v[24:25] neg_lo:[0,1] neg_hi:[0,1]
	v_pk_fma_f32 v[32:33], v[32:33], v[42:43], v[40:41]
	v_pk_fma_f32 v[30:31], v[38:39], v[26:27], v[24:25]
	v_cvt_pk_bf16_f32 v25, v28, v29
	v_add_u32_e32 v28, s24, v186
	v_ashrrev_i32_e32 v29, 31, v28
	v_lshlrev_b64 v[28:29], 11, v[28:29]
	v_lshl_add_u64 v[28:29], s[18:19], 0, v[28:29]
	v_lshl_add_u64 v[28:29], v[28:29], 0, s[40:41]
	s_ashr_i32 s29, s25, 8
	v_and_b32_e32 v185, 15, v187
	v_cvt_pk_bf16_f32 v24, v32, v33
	v_cvt_pk_bf16_f32 v26, v34, v35
	v_cvt_pk_bf16_f32 v27, v30, v31
	v_lshl_add_u64 v[28:29], v[28:29], 0, v[144:145]
	s_lshl_b32 s18, s29, 5
	global_store_dwordx4 v[28:29], v[24:27], off
	v_and_b32_e32 v141, 48, v187
	s_waitcnt lgkmcnt(0)
	s_barrier
	v_or_b32_e32 v24, s18, v185
	v_mul_u32_u24_e32 v145, s50, v24
	v_add3_u32 v60, s5, v141, v145
	s_bfe_u32 s28, s25, 0x20006
	ds_read_b128 v[24:27], v60
	v_lshl_or_b32 v126, s28, 4, v185
	v_mad_u32_u24 v143, v126, s50, 0
	v_add_u32_e32 v189, v143, v141
	v_add3_u32 v64, s7, v141, v145
	ds_read_b128 v[28:31], v189
	ds_read_b128 v[32:35], v64
	ds_read_b128 v[36:39], v189 offset:64
	ds_read_b128 v[40:43], v60 offset:64
	ds_read_b128 v[44:47], v189 offset:9216
	ds_read_b128 v[48:51], v189 offset:9280
	ds_read_b128 v[52:55], v64 offset:64
	ds_read_b128 v[56:59], v60 offset:2304
	ds_read_b128 v[60:63], v60 offset:2368
	s_waitcnt lgkmcnt(4)
	v_mfma_f32_16x16x32_bf16 v[32:35], v[32:35], v[44:47], 0
	v_bfe_u32 v137, v187, 4, 2
	v_lshlrev_b32_e32 v139, 2, v137
	v_or_b32_e32 v146, s18, v139
	v_mfma_f32_16x16x32_bf16 v[24:27], v[24:27], v[28:31], 0
	v_lshlrev_b32_e32 v147, 1, v146
	s_lshl_b32 s20, s28, 8
	s_add_i32 s20, s20, 0
	s_waitcnt lgkmcnt(1)
	v_mfma_f32_16x16x32_bf16 v[28:31], v[56:59], v[28:31], 0
	ds_read_b128 v[56:59], v64 offset:2304
	ds_read_b128 v[64:67], v64 offset:2368
	s_add_i32 s20, s20, 0x1b400
	v_cmp_eq_u32_e64 s[18:19], 15, v185
	v_mfma_f32_16x16x32_bf16 v[72:75], v[52:55], v[48:51], v[32:35]
	v_lshl_add_u32 v191, v146, 2, s20
	s_nop 1
	v_lshlrev_b32_e32 v34, 2, v146
	v_add_u32_e32 v35, 0, v34
	v_mfma_f32_16x16x32_bf16 v[40:43], v[40:43], v[36:39], v[24:27]
	v_add_u32_e32 v32, 0x24900, v35
	ds_read_b128 v[84:87], v32
	s_waitcnt lgkmcnt(3)
	v_mfma_f32_16x16x32_bf16 v[24:27], v[60:63], v[36:39], v[28:31]
	v_lshlrev_b32_e32 v36, 8, v126
	s_nop 1
	v_add_u32_e32 v28, 0x24800, v35
	ds_read_b128 v[28:31], v28
	s_waitcnt lgkmcnt(3)
	v_mfma_f32_16x16x32_bf16 v[44:47], v[56:59], v[44:47], 0
	s_waitcnt lgkmcnt(0)
; __device__ __forceinline__ void phase_prep(const Params& p, unsigned char* shm) {
;     ...
;             const bf16_t* zc = zs + (tk + 1) * LZS; const bf16_t* zp = zs + tk * LZS;
; #pragma unroll
;             for (int n = 0; n < 2; ++n) {
;                 const int c4 = 32 * chh + 16 * n + 4 * fq;
;                 const f32x4 d = *(const f32x4*)(prm + c4) + accd[n], al = *(const f32x4*)(prm + 64 + c4) + acca[n];
; { const f32x2 s0 = sigmoid2((f32x2){d[0], d[1]}), s1 = sigmoid2((f32x2){d[2], d[3]}), a0 = sigmoid2((f32x2){al[0], al[1]}), a1 = sigmoid2((f32x2){al[2], al[3]});
;                   lw[n] = (f32x4){s0.x, s0.y, s1.x, s1.y} * (-0.87503886f); av[n] = (f32x4){a0.x, a0.y, a1.x, a1.y}; }
;                 { const f32x4 vc = ld_bf4(zc + 128 + c4), vp = ld_bf4(zp + 128 + c4); vm[n] = vc + *(const f32x4*)(prm + 256 + c4) * (vp - vc); }
;                 const f32x4 kc = ld_bf4(zc + 64 + c4), kpv = ld_bf4(zp + 64 + c4);
;                 const f32x4 k = kc + *(const f32x4*)(prm + 192 + c4) * (kpv - kc);
;                 kkv[n] = k * *(const f32x4*)(prm + 320 + c4);
;                 kp[n] = k * (1.0f + (av[n] - 1.0f) * *(const f32x4*)(prm + 384 + c4));
;                 const f32x4 rc = ld_bf4(zc + c4), rp = ld_bf4(zp + c4);
;                 rm[n] = rc + *(const f32x4*)(prm + 128 + c4) * (rp - rc);
;                 const f32x4 rkw = rm[n] * kp[n] * *(const f32x4*)(prm + 448 + c4);
;                 { const f32x4 sq = kkv[n] * kkv[n]; nrm += (sq[0] + sq[1]) + (sq[2] + sq[3]); }
;                 rk += rkw[0] + rkw[1] + rkw[2] + rkw[3];
; #pragma unroll
;                 for (int j = 0; j < 4; ++j) {
;                     float x = lw[n][j];
;                     x += __int_as_float(__builtin_amdgcn_update_dpp(0, __float_as_int(x), 0x111, 0xf, 0xf, false));
;                     x += __int_as_float(__builtin_amdgcn_update_dpp(0, __float_as_int(x), 0x112, 0xf, 0xf, false));
;                     x += __int_as_float(__builtin_amdgcn_update_dpp(0, __float_as_int(x), 0x114, 0xf, 0xf, false));
;                     x += __int_as_float(__builtin_amdgcn_update_dpp(0, __float_as_int(x), 0x118, 0xf, 0xf, false));
;                     cs[n][j] = x;
;                 }
;                 if (fr == 15) *(f32x4*)(tot + tt * 64 + c4) = cs[n];
	v_pk_add_f32 v[28:29], v[40:41], v[28:29]
	s_nop 0
	v_pk_mul_f32 v[28:29], v[28:29], s[4:5] op_sel_hi:[1,0]
	v_pk_add_f32 v[30:31], v[42:43], v[30:31]
	v_exp_f32_e32 v28, v28
	v_exp_f32_e32 v29, v29
	v_mfma_f32_16x16x32_bf16 v[56:59], v[64:67], v[48:51], v[44:47]
	v_mul_f32_e64 v30, v30, s4
	v_mul_f32_e64 v31, v31, s4
	v_pk_add_f32 v[28:29], v[28:29], 1.0 op_sel_hi:[1,0]
	s_nop 0
	v_rcp_f32_e32 v32, v28
	v_rcp_f32_e32 v33, v29
	v_add3_u32 v28, v143, v36, v147
	v_add_u32_e32 v28, 0xd000, v28
	v_add_u32_e32 v29, s52, v34
	v_add_u32_e32 v34, 0x24b00, v35
	ds_read2_b64 v[52:55], v28 offset0:228 offset1:244
	ds_read2_b64 v[48:51], v28 offset0:194 offset1:212
	ds_read2_b64 v[68:71], v28 offset0:162 offset1:178
	ds_read_b128 v[44:47], v29
	ds_read_b128 v[92:95], v34
	v_add_u32_e32 v29, 0x24d00, v35
	v_add_u32_e32 v34, 0x24e00, v35
	v_exp_f32_e32 v30, v30
	v_exp_f32_e32 v31, v31
	ds_read_b128 v[96:99], v29
	ds_read_b128 v[76:79], v34
	v_add_u32_e32 v29, 0x24a00, v35
	v_add_u32_e32 v34, 0x24f00, v35
	v_pk_mul_f32 v[154:155], v[32:33], s[6:7] op_sel_hi:[1,0]
	ds_read_b128 v[64:67], v29
	ds_read_b128 v[60:63], v34
	v_mov_b32_e32 v34, v127
	v_mov_b32_e32 v35, v127
	v_pk_add_f32 v[30:31], v[30:31], 1.0 op_sel_hi:[1,0]
	v_mov_b32_dpp v34, v154 row_shr:1 row_mask:0xf bank_mask:0xf
	v_mov_b32_dpp v35, v155 row_shr:1 row_mask:0xf bank_mask:0xf
	v_pk_fma_f32 v[32:33], v[32:33], s[6:7], v[34:35] op_sel_hi:[1,0,1]
	v_rcp_f32_e32 v30, v30
	v_rcp_f32_e32 v31, v31
	v_add_f32_dpp v32, v32, v32 row_shr:2 row_mask:0xf bank_mask:0xf bound_ctrl:1
	v_add_f32_dpp v33, v33, v33 row_shr:2 row_mask:0xf bank_mask:0xf bound_ctrl:1
	v_pk_mul_f32 v[152:153], v[30:31], s[6:7] op_sel_hi:[1,0]
	v_mov_b32_e32 v34, v127
	v_mov_b32_e32 v35, v127
	v_add_f32_dpp v32, v32, v32 row_shr:4 row_mask:0xf bank_mask:0xf bound_ctrl:1
	v_add_f32_dpp v33, v33, v33 row_shr:4 row_mask:0xf bank_mask:0xf bound_ctrl:1
	v_mov_b32_dpp v34, v152 row_shr:1 row_mask:0xf bank_mask:0xf
	v_mov_b32_dpp v35, v153 row_shr:1 row_mask:0xf bank_mask:0xf
	v_add_f32_dpp v40, v32, v32 row_shr:8 row_mask:0xf bank_mask:0xf bound_ctrl:1
	v_add_f32_dpp v41, v33, v33 row_shr:8 row_mask:0xf bank_mask:0xf bound_ctrl:1
	v_pk_fma_f32 v[30:31], v[30:31], s[6:7], v[34:35] op_sel_hi:[1,0,1]
	s_nop 1
	v_add_f32_dpp v30, v30, v30 row_shr:2 row_mask:0xf bank_mask:0xf bound_ctrl:1
	v_add_f32_dpp v31, v31, v31 row_shr:2 row_mask:0xf bank_mask:0xf bound_ctrl:1
	s_nop 0
	v_add_f32_dpp v30, v30, v30 row_shr:4 row_mask:0xf bank_mask:0xf bound_ctrl:1
	v_add_f32_dpp v31, v31, v31 row_shr:4 row_mask:0xf bank_mask:0xf bound_ctrl:1
	s_nop 0
	v_add_f32_dpp v42, v30, v30 row_shr:8 row_mask:0xf bank_mask:0xf bound_ctrl:1
	v_add_f32_dpp v43, v31, v31 row_shr:8 row_mask:0xf bank_mask:0xf bound_ctrl:1
	s_and_saveexec_b64 s[20:21], s[18:19]
	ds_write_b128 v191, v[40:43]
	s_or_b64 exec, exec, s[20:21]
	v_or_b32_e32 v29, 16, v146
	v_lshl_add_u32 v190, v29, 2, 0
	v_add_u32_e32 v29, 0x24800, v190
	ds_read_b128 v[30:33], v29
	v_mov_b32_e32 v196, v127
	v_mov_b32_e32 v197, v127
	v_add_u32_e32 v29, 0x24900, v190
	ds_read_b128 v[116:119], v29
	s_waitcnt lgkmcnt(1)
	v_pk_add_f32 v[24:25], v[24:25], v[30:31]
	v_pk_add_f32 v[26:27], v[26:27], v[32:33]
	v_pk_mul_f32 v[24:25], v[24:25], s[4:5] op_sel_hi:[1,0]
	v_pk_mul_f32 v[26:27], v[26:27], s[4:5] op_sel_hi:[1,0]
	v_exp_f32_e32 v24, v24
	v_exp_f32_e32 v25, v25
	v_exp_f32_e32 v26, v26
	v_exp_f32_e32 v27, v27
	v_add_u32_e32 v29, 0x24c00, v190
	v_pk_add_f32 v[24:25], v[24:25], 1.0 op_sel_hi:[1,0]
	v_add_u32_e32 v80, 0x24b00, v190
	v_rcp_f32_e32 v24, v24
	v_rcp_f32_e32 v25, v25
	v_pk_add_f32 v[26:27], v[26:27], 1.0 op_sel_hi:[1,0]
	ds_read2_b64 v[36:39], v28 offset0:232 offset1:248
	ds_read2_b64 v[32:35], v28 offset0:198 offset1:216
	v_rcp_f32_e32 v26, v26
	v_pk_mul_f32 v[150:151], v[24:25], s[6:7] op_sel_hi:[1,0]
	v_rcp_f32_e32 v27, v27
	ds_read2_b64 v[100:103], v28 offset0:166 offset1:182
	v_mov_b32_dpp v196, v150 row_shr:1 row_mask:0xf bank_mask:0xf
	v_mov_b32_dpp v197, v151 row_shr:1 row_mask:0xf bank_mask:0xf
	v_pk_fma_f32 v[24:25], v[24:25], s[6:7], v[196:197] op_sel_hi:[1,0,1]
	v_mov_b32_e32 v196, v127
	v_mov_b32_e32 v197, v127
	v_pk_mul_f32 v[148:149], v[26:27], s[6:7] op_sel_hi:[1,0]
	v_add_f32_dpp v24, v24, v24 row_shr:2 row_mask:0xf bank_mask:0xf bound_ctrl:1
	v_add_f32_dpp v25, v25, v25 row_shr:2 row_mask:0xf bank_mask:0xf bound_ctrl:1
	ds_read_b128 v[28:31], v29
	ds_read_b128 v[108:111], v80
	v_add_f32_dpp v24, v24, v24 row_shr:4 row_mask:0xf bank_mask:0xf bound_ctrl:1
	v_add_f32_dpp v25, v25, v25 row_shr:4 row_mask:0xf bank_mask:0xf bound_ctrl:1
	v_add_u32_e32 v80, 0x24d00, v190
	v_mov_b32_dpp v196, v148 row_shr:1 row_mask:0xf bank_mask:0xf
	v_mov_b32_dpp v197, v149 row_shr:1 row_mask:0xf bank_mask:0xf
	v_add_f32_dpp v24, v24, v24 row_shr:8 row_mask:0xf bank_mask:0xf bound_ctrl:1
	v_add_f32_dpp v25, v25, v25 row_shr:8 row_mask:0xf bank_mask:0xf bound_ctrl:1
	v_add_u32_e32 v81, 0x24e00, v190
	v_pk_fma_f32 v[26:27], v[26:27], s[6:7], v[196:197] op_sel_hi:[1,0,1]
	ds_read_b128 v[112:115], v80
	ds_read_b128 v[104:107], v81
	v_add_u32_e32 v80, 0x24a00, v190
	v_add_u32_e32 v81, 0x24f00, v190
	v_add_f32_dpp v26, v26, v26 row_shr:2 row_mask:0xf bank_mask:0xf bound_ctrl:1
	v_add_f32_dpp v27, v27, v27 row_shr:2 row_mask:0xf bank_mask:0xf bound_ctrl:1
	ds_read_b128 v[88:91], v80
	ds_read_b128 v[80:83], v81
	v_add_f32_dpp v26, v26, v26 row_shr:4 row_mask:0xf bank_mask:0xf bound_ctrl:1
	v_add_f32_dpp v27, v27, v27 row_shr:4 row_mask:0xf bank_mask:0xf bound_ctrl:1
	s_nop 0
	v_add_f32_dpp v26, v26, v26 row_shr:8 row_mask:0xf bank_mask:0xf bound_ctrl:1
	v_add_f32_dpp v27, v27, v27 row_shr:8 row_mask:0xf bank_mask:0xf bound_ctrl:1
; __device__ __forceinline__ f32x4 ld_bf4(const bf16_t* p) { const u32x2 u = *(const u32x2*)p; return (f32x4){bf_lo(u.x), bf_hi(u.x), bf_lo(u.y), bf_hi(u.y)}; }
; #define LDS_BARRIER() do { asm volatile("s_waitcnt lgkmcnt(0)" ::: "memory"); __builtin_amdgcn_s_barrier(); asm volatile("" ::: "memory"); } while (0)
; __device__ __forceinline__ void phase_prep(const Params& p, unsigned char* shm) {
;     ...
;                 { const f32x4 vc = ld_bf4(zc + 128 + c4), vp = ld_bf4(zp + 128 + c4); vm[n] = vc + *(const f32x4*)(prm + 256 + c4) * (vp - vc); }
;                 const f32x4 kc = ld_bf4(zc + 64 + c4), kpv = ld_bf4(zp + 64 + c4);
;                 const f32x4 k = kc + *(const f32x4*)(prm + 192 + c4) * (kpv - kc);
;                 kkv[n] = k * *(const f32x4*)(prm + 320 + c4);
;                 kp[n] = k * (1.0f + (av[n] - 1.0f) * *(const f32x4*)(prm + 384 + c4));
;                 const f32x4 rc = ld_bf4(zc + c4), rp = ld_bf4(zp + c4);
;                 rm[n] = rc + *(const f32x4*)(prm + 128 + c4) * (rp - rc);
;                 const f32x4 rkw = rm[n] * kp[n] * *(const f32x4*)(prm + 448 + c4);
;                 { const f32x4 sq = kkv[n] * kkv[n]; nrm += (sq[0] + sq[1]) + (sq[2] + sq[3]); }
;                 rk += rkw[0] + rkw[1] + rkw[2] + rkw[3];
; #pragma unroll
;                 for (int j = 0; j < 4; ++j) {
;                     float x = lw[n][j];
;                     x += __int_as_float(__builtin_amdgcn_update_dpp(0, __float_as_int(x), 0x111, 0xf, 0xf, false));
;                     x += __int_as_float(__builtin_amdgcn_update_dpp(0, __float_as_int(x), 0x112, 0xf, 0xf, false));
;                     x += __int_as_float(__builtin_amdgcn_update_dpp(0, __float_as_int(x), 0x114, 0xf, 0xf, false));
;                     x += __int_as_float(__builtin_amdgcn_update_dpp(0, __float_as_int(x), 0x118, 0xf, 0xf, false));
;                     cs[n][j] = x;
;                 }
;                 if (fr == 15) *(f32x4*)(tot + tt * 64 + c4) = cs[n];
;             }
;             nrm += __shfl_xor(nrm, 16); nrm += __shfl_xor(nrm, 32);
;             rk += __shfl_xor(rk, 16); rk += __shfl_xor(rk, 32);
;             if (fq == 0) { red[wid * 16 + fr] = nrm; red[128 + wid * 16 + fr] = rk; }
;         }
;         LDS_BARRIER();
	s_and_saveexec_b64 s[20:21], s[18:19]
	ds_write_b128 v191, v[24:27] offset:64
	s_or_b64 exec, exec, s[20:21]
	v_pk_add_f32 v[74:75], v[74:75], v[86:87]
	v_pk_add_f32 v[72:73], v[72:73], v[84:85]
	v_pk_mul_f32 v[74:75], v[74:75], s[4:5] op_sel_hi:[1,0]
	v_pk_mul_f32 v[72:73], v[72:73], s[4:5] op_sel_hi:[1,0]
	v_exp_f32_e32 v74, v74
	v_exp_f32_e32 v75, v75
	v_exp_f32_e32 v72, v72
	v_exp_f32_e32 v73, v73
	v_lshlrev_b32_e32 v84, 16, v52
	v_pk_add_f32 v[74:75], v[74:75], 1.0 op_sel_hi:[1,0]
	v_and_b32_e32 v85, 0xffff0000, v52
	v_pk_add_f32 v[72:73], v[72:73], 1.0 op_sel_hi:[1,0]
	v_rcp_f32_e32 v74, v74
	v_rcp_f32_e32 v75, v75
	v_rcp_f32_e32 v72, v72
	v_rcp_f32_e32 v73, v73
	v_lshlrev_b32_e32 v52, 16, v53
	v_and_b32_e32 v53, 0xffff0000, v53
	v_lshlrev_b32_e32 v86, 16, v70
	v_and_b32_e32 v87, 0xffff0000, v70
	v_lshlrev_b32_e32 v70, 16, v71
	v_and_b32_e32 v71, 0xffff0000, v71
	v_sub_f32_e32 v71, v71, v53
	v_sub_f32_e32 v70, v70, v52
	v_pk_fma_f32 v[52:53], v[94:95], v[70:71], v[52:53]
	v_pk_add_f32 v[94:95], v[74:75], -1.0 op_sel_hi:[1,0]
	v_sub_f32_e32 v87, v87, v85
	v_sub_f32_e32 v86, v86, v84
	v_pk_add_f32 v[70:71], v[72:73], -1.0 op_sel_hi:[1,0]
	v_pk_fma_f32 v[78:79], v[78:79], v[94:95], 1.0 op_sel_hi:[1,1,0]
	v_pk_fma_f32 v[92:93], v[92:93], v[86:87], v[84:85]
	v_pk_mul_f32 v[84:85], v[98:99], v[52:53]
	v_pk_fma_f32 v[70:71], v[76:77], v[70:71], 1.0 op_sel_hi:[1,1,0]
	v_pk_mul_f32 v[76:77], v[52:53], v[78:79]
	v_lshlrev_b32_e32 v52, 16, v50
	v_and_b32_e32 v53, 0xffff0000, v50
	v_lshlrev_b32_e32 v78, 16, v68
	v_and_b32_e32 v68, 0xffff0000, v68
	v_pk_mul_f32 v[86:87], v[96:97], v[92:93]
	v_pk_mul_f32 v[70:71], v[92:93], v[70:71]
	v_lshlrev_b32_e32 v50, 16, v51
	v_and_b32_e32 v51, 0xffff0000, v51
	v_lshlrev_b32_e32 v92, 16, v69
	v_and_b32_e32 v79, 0xffff0000, v69
	v_sub_f32_e32 v69, v68, v53
	v_sub_f32_e32 v68, v78, v52
	v_sub_f32_e32 v79, v79, v51
	v_sub_f32_e32 v78, v92, v50
	v_pk_fma_f32 v[64:65], v[64:65], v[68:69], v[52:53]
	v_pk_fma_f32 v[66:67], v[66:67], v[78:79], v[50:51]
	v_pk_mul_f32 v[50:51], v[70:71], v[64:65]
	v_pk_mul_f32 v[52:53], v[76:77], v[66:67]
	v_pk_mul_f32 v[50:51], v[60:61], v[50:51]
	v_pk_mul_f32 v[52:53], v[62:63], v[52:53]
	v_add_f32_e32 v50, v50, v51
	v_add_f32_e32 v50, v52, v50
	v_add_f32_e32 v50, v53, v50
	v_add_f32_e32 v93, 0, v50
	s_waitcnt lgkmcnt(9)
	v_pk_add_f32 v[50:51], v[58:59], v[118:119]
	v_pk_add_f32 v[52:53], v[56:57], v[116:117]
	v_pk_mul_f32 v[50:51], v[50:51], s[4:5] op_sel_hi:[1,0]
	v_pk_mul_f32 v[52:53], v[52:53], s[4:5] op_sel_hi:[1,0]
	v_exp_f32_e32 v56, v50
	v_exp_f32_e32 v52, v52
	v_exp_f32_e32 v53, v53
	v_exp_f32_e32 v57, v51
	v_pk_mul_f32 v[60:61], v[84:85], v[84:85]
	v_pk_mul_f32 v[62:63], v[86:87], v[86:87]
	v_pk_add_f32 v[50:51], v[52:53], 1.0 op_sel_hi:[1,0]
	v_pk_add_f32 v[52:53], v[56:57], 1.0 op_sel_hi:[1,0]
	v_rcp_f32_e32 v50, v50
	v_rcp_f32_e32 v51, v51
	v_rcp_f32_e32 v52, v52
	v_rcp_f32_e32 v53, v53
	v_add_f32_e32 v62, v62, v63
	v_add_f32_e32 v60, v60, v61
	s_waitcnt lgkmcnt(8)
	v_lshlrev_b32_e32 v56, 16, v36
	v_and_b32_e32 v57, 0xffff0000, v36
	v_lshlrev_b32_e32 v36, 16, v37
	v_and_b32_e32 v37, 0xffff0000, v37
	s_waitcnt lgkmcnt(6)
	v_lshlrev_b32_e32 v58, 16, v103
	v_and_b32_e32 v59, 0xffff0000, v103
	v_add_f32_e32 v92, v62, v60
	v_lshlrev_b32_e32 v60, 16, v102
	v_and_b32_e32 v61, 0xffff0000, v102
	v_sub_f32_e32 v59, v59, v37
	v_sub_f32_e32 v58, v58, v36
	v_sub_f32_e32 v61, v61, v57
	v_sub_f32_e32 v60, v60, v56
	s_waitcnt lgkmcnt(4)
	v_pk_fma_f32 v[62:63], v[110:111], v[58:59], v[36:37]
	v_pk_add_f32 v[36:37], v[50:51], -1.0 op_sel_hi:[1,0]
	v_pk_add_f32 v[68:69], v[52:53], -1.0 op_sel_hi:[1,0]
	v_pk_fma_f32 v[56:57], v[108:109], v[60:61], v[56:57]
	s_waitcnt lgkmcnt(2)
	v_pk_fma_f32 v[68:69], v[106:107], v[68:69], 1.0 op_sel_hi:[1,1,0]
	v_pk_fma_f32 v[36:37], v[104:105], v[36:37], 1.0 op_sel_hi:[1,1,0]
	v_pk_mul_f32 v[58:59], v[114:115], v[62:63]
	v_pk_mul_f32 v[60:61], v[112:113], v[56:57]
	v_pk_mul_f32 v[36:37], v[56:57], v[36:37]
	v_pk_mul_f32 v[56:57], v[62:63], v[68:69]
	v_lshlrev_b32_e32 v62, 16, v34
	v_and_b32_e32 v63, 0xffff0000, v34
	v_lshlrev_b32_e32 v34, 16, v35
	v_and_b32_e32 v35, 0xffff0000, v35
	v_lshlrev_b32_e32 v68, 16, v100
	v_and_b32_e32 v69, 0xffff0000, v100
	v_lshlrev_b32_e32 v78, 16, v101
	v_and_b32_e32 v79, 0xffff0000, v101
	v_sub_f32_e32 v69, v69, v63
	v_sub_f32_e32 v68, v68, v62
	v_sub_f32_e32 v79, v79, v35
	v_sub_f32_e32 v78, v78, v34
	s_waitcnt lgkmcnt(1)
	v_pk_fma_f32 v[34:35], v[90:91], v[78:79], v[34:35]
	v_pk_fma_f32 v[62:63], v[88:89], v[68:69], v[62:63]
	v_pk_mul_f32 v[78:79], v[56:57], v[34:35]
	v_pk_mul_f32 v[68:69], v[36:37], v[62:63]
	s_waitcnt lgkmcnt(0)
	v_pk_mul_f32 v[78:79], v[82:83], v[78:79]
	v_pk_mul_f32 v[68:69], v[80:81], v[68:69]
	v_pk_mul_f32 v[80:81], v[58:59], v[58:59]
	v_pk_mul_f32 v[82:83], v[60:61], v[60:61]
	v_add_f32_e32 v80, v80, v81
	v_add_f32_e32 v82, v82, v83
	v_add_f32_e32 v80, v82, v80
	v_and_b32_e32 v82, 64, v180
	v_xor_b32_e32 v81, 16, v180
	v_add_u32_e32 v82, 64, v82
	v_add_f32_e32 v68, v68, v69
	v_cmp_lt_i32_e32 vcc, v81, v82
	v_add_f32_e32 v68, v78, v68
	v_add_f32_e32 v68, v79, v68
	v_cndmask_b32_e32 v81, v180, v81, vcc
	v_add_f32_e32 v80, v92, v80
	v_lshlrev_b32_e32 v81, 2, v81
	v_add_f32_e32 v68, v93, v68
	ds_bpermute_b32 v83, v81, v80
	ds_bpermute_b32 v79, v81, v68
	v_xor_b32_e32 v78, 32, v180
	v_cmp_lt_i32_e32 vcc, v78, v82
	s_ashr_i32 s71, s25, 6
	s_waitcnt lgkmcnt(1)
	v_add_f32_e32 v69, v80, v83
	v_cndmask_b32_e32 v78, v180, v78, vcc
	v_lshlrev_b32_e32 v78, 2, v78
	s_waitcnt lgkmcnt(0)
	v_add_f32_e32 v79, v68, v79
	ds_bpermute_b32 v80, v78, v69
	ds_bpermute_b32 v81, v78, v79
	v_and_b32_e32 v68, 63, v187
	s_ashr_i32 s27, s26, 31
	v_cmp_gt_u32_e32 vcc, 16, v68
	s_waitcnt lgkmcnt(1)
	v_add_f32_e32 v78, v69, v80
	s_waitcnt lgkmcnt(0)
	v_add_f32_e32 v69, v79, v81
	s_lshl_b32 s72, s71, 4
	s_and_saveexec_b64 s[20:21], vcc
	s_lshl_b32 s23, s72, 2
	s_add_i32 s23, s23, 0
	v_lshl_add_u32 v79, v185, 2, s23
	v_add_u32_e32 v79, 0x1b000, v79
	ds_write2st64_b32 v79, v78, v69 offset1:2
	s_or_b64 exec, exec, s[20:21]
	s_xor_b32 s20, s72, 64
	s_lshl_b32 s20, s20, 2
	s_add_i32 s20, s20, 0
	v_lshl_add_u32 v81, v185, 2, s20
	s_waitcnt lgkmcnt(0)
	s_barrier
; __device__ __forceinline__ void st_bf4(bf16_t* p, f32x4 v) { u32x2 u; u.x = pk_bf16(v[0], v[1]); u.y = pk_bf16(v[2], v[3]); *(u32x2*)p = u; }
; __device__ __forceinline__ void phase_prep(const Params& p, unsigned char* shm) {
;     ...
;         {
;             nrm += red[(wid ^ 4) * 16 + fr]; rk += red[128 + (wid ^ 4) * 16 + fr];
;             const float inv = 1.0f / fmaxf(sqrtf(nrm), 1e-12f);
;             p.PRK[(size_t)row * 16 + h] = rk;
; #pragma unroll
;             for (int n = 0; n < 2; ++n) {
;                 const int c4 = 32 * chh + 16 * n + 4 * fq;
;                 f32x4 pre = (f32x4){0.f, 0.f, 0.f, 0.f}, total = (f32x4){0.f, 0.f, 0.f, 0.f};
; #pragma unroll
;                 for (int t2 = 0; t2 < 4; ++t2) { const f32x4 x = *(const f32x4*)(tot + t2 * 64 + c4); total += x; if (t2 < tt) pre += x; }
;                 const f32x4 csum = pre + cs[n];
;                 f32x4 eg, eng, egm, etc; const f32x4 ncs = -csum, cml = csum - lw[n], tmc = total - csum;
; #pragma unroll
;                 for (int j = 0; j < 4; ++j) { eg[j] = __builtin_amdgcn_exp2f(csum[j]); eng[j] = __builtin_amdgcn_exp2f(ncs[j]); egm[j] = __builtin_amdgcn_exp2f(cml[j]); etc[j] = __builtin_amdgcn_exp2f(tmc[j]); }
;                 const f32x4 kkn = kkv[n] * inv, bb = kkn * av[n];
;                 const f32x4 qt = rm[n] * eg, kt = kp[n] * eng, bt = bb * eng, kkt = kkn * egm, kpp = kp[n] * etc, bpp = bb * etc;
;                 st_bf4(Qt + tk * LD + c4, qt); st_bf4(Kt + tk * LD + c4, kt); st_bf4(Bt + tk * LD + c4, bt);
;                 const u32x2 kkw = pk_bf4(kkt), vmw = pk_bf4(vm[n]), kpw = pk_bf4(kpp), bpw = pk_bf4(bpp);
;                 *(u32x2*)(KKt + tk * LD + c4) = kkw;
;                 { bf16_t* d = KKtT + c4 * LD + tk; d[0] = (bf16_t)kkw.x; d[LD] = (bf16_t)(kkw.x >> 16); d[2 * LD] = (bf16_t)kkw.y; d[3 * LD] = (bf16_t)(kkw.y >> 16); }
;                 { bf16_t* d = VmT + c4 * LD + tk; d[0] = (bf16_t)vmw.x; d[LD] = (bf16_t)(vmw.x >> 16); d[2 * LD] = (bf16_t)vmw.y; d[3 * LD] = (bf16_t)(vmw.y >> 16); }
;                 { bf16_t* d = KpT + c4 * LD + tk; d[0] = (bf16_t)kpw.x; d[LD] = (bf16_t)(kpw.x >> 16); d[2 * LD] = (bf16_t)kpw.y; d[3 * LD] = (bf16_t)(kpw.y >> 16); }
;                 { bf16_t* d = BpT + c4 * LD + tk; d[0] = (bf16_t)bpw.x; d[LD] = (bf16_t)(bpw.x >> 16); d[2 * LD] = (bf16_t)bpw.y; d[3 * LD] = (bf16_t)(bpw.y >> 16); }
	v_add_u32_e32 v81, 0x1b000, v81
	ds_read2st64_b32 v[88:89], v81 offset1:2
	v_and_b32_e32 v83, 0xffff0000, v54
	v_lshlrev_b32_e32 v79, 16, v48
	v_and_b32_e32 v48, 0xffff0000, v48
	v_lshlrev_b32_e32 v81, 16, v49
	v_and_b32_e32 v90, 0xffff0000, v49
	v_sub_f32_e32 v49, v48, v83
	s_waitcnt lgkmcnt(0)
	v_add_f32_e32 v48, v78, v88
	v_mul_f32_e32 v78, 0x4f800000, v48
	v_cmp_gt_f32_e32 vcc, s53, v48
	v_lshlrev_b32_e32 v82, 16, v54
	v_lshlrev_b32_e32 v54, 16, v55
	v_cndmask_b32_e32 v88, v48, v78, vcc
	v_sqrt_f32_e32 v91, v88
	v_and_b32_e32 v55, 0xffff0000, v55
	v_sub_f32_e32 v78, v81, v54
	v_sub_f32_e32 v48, v79, v82
	v_add_u32_e32 v81, -1, v91
	v_sub_f32_e32 v79, v90, v55
	v_fma_f32 v90, -v81, v91, v88
	v_cmp_ge_f32_e64 s[20:21], 0, v90
	v_add_u32_e32 v90, 1, v91
	v_pk_fma_f32 v[82:83], v[44:45], v[48:49], v[82:83]
	v_cndmask_b32_e64 v81, v91, v81, s[20:21]
	v_fma_f32 v91, -v90, v91, v88
	v_cmp_lt_f32_e64 s[20:21], 0, v91
	v_pk_fma_f32 v[54:55], v[46:47], v[78:79], v[54:55]
	v_or_b32_e32 v80, s24, v126
	v_cndmask_b32_e64 v81, v81, v90, s[20:21]
	v_mul_f32_e32 v90, 0x37800000, v81
	v_cndmask_b32_e32 v81, v81, v90, vcc
	v_cmp_class_f32_e32 vcc, v88, v181
	s_lshl_b32 s40, s22, 2
	v_add_f32_e32 v45, v69, v89
	v_cndmask_b32_e32 v81, v81, v88, vcc
	v_max_f32_e32 v81, 0x2b8cbccc, v81
	v_div_scale_f32 v88, s[20:21], v81, v81, 1.0
	v_rcp_f32_e32 v90, v88
	s_mov_b64 s[20:21], s[92:93]
	s_cmp_eq_u32 s28, 0
	s_cselect_b64 s[24:25], -1, 0
	v_fma_f32 v44, -v88, v90, 1.0
	v_fmac_f32_e32 v90, v44, v90
	v_div_scale_f32 v44, vcc, 1.0, v81, 1.0
	v_mul_f32_e32 v46, v44, v90
	v_fma_f32 v47, -v88, v46, v44
	v_fmac_f32_e32 v46, v47, v90
	v_fma_f32 v44, -v88, v46, v44
	v_div_fmas_f32 v44, v44, v90, v46
	v_div_fixup_f32 v44, v44, v81, 1.0
	v_ashrrev_i32_e32 v81, 31, v80
	v_lshlrev_b64 v[46:47], 6, v[80:81]
	s_waitcnt lgkmcnt(0)
	v_lshl_add_u64 v[46:47], s[20:21], 0, v[46:47]
	v_lshl_add_u64 v[46:47], v[46:47], 0, s[40:41]
	global_store_dword v[46:47], v45, off
	v_lshl_add_u32 v46, v146, 2, 0
	v_add_u32_e32 v69, 0x1b400, v46
	ds_read_b128 v[46:49], v69
	ds_read_b128 v[78:81], v69 offset:256
	s_lshl_b64 s[22:23], s[26:27], 8
	s_cmp_gt_u32 s28, 1
	ds_read_b128 v[88:91], v69 offset:512
	s_waitcnt lgkmcnt(2)
	v_pk_add_f32 v[48:49], v[48:49], 0 op_sel_hi:[1,0]
	s_cselect_b64 vcc, -1, 0
	v_cndmask_b32_e64 v93, v49, 0, s[24:25]
	v_cndmask_b32_e64 v92, v48, 0, s[24:25]
	s_waitcnt lgkmcnt(1)
	v_pk_add_f32 v[94:95], v[80:81], v[92:93]
	v_pk_add_f32 v[46:47], v[46:47], 0 op_sel_hi:[1,0]
	v_cndmask_b32_e32 v97, v93, v95, vcc
	v_cndmask_b32_e32 v96, v92, v94, vcc
	ds_read_b128 v[92:95], v69 offset:768
	v_cndmask_b32_e64 v101, v47, 0, s[24:25]
	v_cndmask_b32_e64 v100, v46, 0, s[24:25]
	v_pk_add_f32 v[46:47], v[46:47], v[78:79]
	v_pk_add_f32 v[78:79], v[78:79], v[100:101]
	s_cmp_eq_u32 s28, 3
	v_cndmask_b32_e32 v79, v101, v79, vcc
	v_cndmask_b32_e32 v78, v100, v78, vcc
	s_waitcnt lgkmcnt(1)
	v_pk_add_f32 v[98:99], v[90:91], v[96:97]
	s_cselect_b64 s[20:21], -1, 0
	v_pk_add_f32 v[48:49], v[48:49], v[80:81]
	v_pk_add_f32 v[80:81], v[46:47], v[88:89]
	v_pk_add_f32 v[46:47], v[88:89], v[78:79]
	v_pk_add_f32 v[48:49], v[48:49], v[90:91]
	v_cndmask_b32_e64 v89, v97, v99, s[20:21]
	v_cndmask_b32_e64 v88, v96, v98, s[20:21]
	v_cndmask_b32_e64 v79, v79, v47, s[20:21]
	v_cndmask_b32_e64 v78, v78, v46, s[20:21]
	s_waitcnt lgkmcnt(0)
	v_pk_add_f32 v[46:47], v[48:49], v[94:95]
	v_pk_add_f32 v[48:49], v[80:81], v[92:93]
	v_pk_add_f32 v[42:43], v[42:43], v[88:89]
	v_pk_add_f32 v[40:41], v[40:41], v[78:79]
	v_sub_f32_e32 v91, v46, v42
	v_sub_f32_e32 v79, v48, v40
	v_sub_f32_e32 v69, v47, v43
	v_sub_f32_e32 v89, v49, v41
	v_exp_f32_e32 v78, v40
	v_exp_f32_e64 v80, -v40
	v_sub_f32_e32 v40, v40, v154
	v_exp_f32_e32 v88, v79
	v_exp_f32_e32 v79, v41
	v_exp_f32_e64 v81, -v41
	v_sub_f32_e32 v41, v41, v155
	v_exp_f32_e32 v90, v42
	v_exp_f32_e64 v92, -v42
	v_sub_f32_e32 v42, v42, v152
	v_exp_f32_e32 v94, v91
	v_exp_f32_e32 v91, v43
	v_exp_f32_e64 v93, -v43
	v_sub_f32_e32 v43, v43, v153
	v_mul_u32_u24_e32 v45, 0x48, v126
	v_exp_f32_e32 v40, v40
	v_exp_f32_e32 v41, v41
	v_exp_f32_e32 v42, v42
	v_exp_f32_e32 v43, v43
	v_lshlrev_b32_e32 v45, 1, v45
	v_pk_mul_f32 v[84:85], v[84:85], v[44:45] op_sel_hi:[1,0]
	v_pk_mul_f32 v[86:87], v[86:87], v[44:45] op_sel_hi:[1,0]
	v_exp_f32_e32 v89, v89
	v_pk_mul_f32 v[72:73], v[72:73], v[86:87]
	v_pk_mul_f32 v[74:75], v[74:75], v[84:85]
	v_pk_mul_f32 v[66:67], v[66:67], v[90:91]
	v_pk_mul_f32 v[64:65], v[64:65], v[78:79]
	v_pk_mul_f32 v[78:79], v[76:77], v[92:93]
	v_pk_mul_f32 v[90:91], v[70:71], v[80:81]
	v_exp_f32_e32 v95, v69
	v_pk_mul_f32 v[92:93], v[74:75], v[92:93]
	v_pk_mul_f32 v[80:81], v[72:73], v[80:81]
	v_pk_mul_f32 v[42:43], v[84:85], v[42:43]
	v_pk_mul_f32 v[84:85], v[86:87], v[40:41]
	v_add3_u32 v40, 0, v45, v147
	v_cvt_pk_bf16_f32 v64, v64, v65
	v_cvt_pk_bf16_f32 v65, v66, v67
	v_cvt_pk_bf16_f32 v66, v90, v91
	v_cvt_pk_bf16_f32 v67, v78, v79
	ds_write2st64_b64 v40, v[64:65], v[66:67] offset0:72 offset1:90
	v_cvt_pk_bf16_f32 v64, v80, v81
	v_cvt_pk_bf16_f32 v65, v92, v93
	v_cvt_pk_bf16_f32 v66, v84, v85
	v_cvt_pk_bf16_f32 v67, v42, v43
	v_lshlrev_b32_e32 v102, 1, v126
	ds_write2st64_b64 v40, v[64:65], v[66:67] offset0:108 offset1:126
	v_mul_u32_u24_e32 v64, s50, v146
	v_pk_mul_f32 v[70:71], v[70:71], v[88:89]
	v_pk_mul_f32 v[72:73], v[72:73], v[88:89]
	v_cvt_pk_bf16_f32 v41, v82, v83
	v_add3_u32 v42, s55, v102, v64
	v_add3_u32 v43, s56, v102, v64
	s_cmp_lg_u32 s28, 0
	v_pk_mul_f32 v[76:77], v[76:77], v[94:95]
	v_pk_mul_f32 v[74:75], v[74:75], v[94:95]
	v_cvt_pk_bf16_f32 v45, v54, v55
	v_cvt_pk_bf16_f32 v55, v70, v71
	v_cvt_pk_bf16_f32 v70, v72, v73
	ds_write_b16 v42, v66
	ds_write_b16_d16_hi v42, v66 offset:144
	ds_write_b16 v42, v67 offset:288
	ds_write_b16_d16_hi v42, v67 offset:432
	ds_write_b16 v43, v41
	ds_write_b16_d16_hi v43, v41 offset:144
	ds_write_b16 v43, v45 offset:288
	ds_write_b16_d16_hi v43, v45 offset:432
	v_add3_u32 v54, s57, v102, v64
	v_add3_u32 v41, s58, v102, v64
	v_cvt_pk_bf16_f32 v69, v76, v77
	v_cvt_pk_bf16_f32 v71, v74, v75
	ds_write_b16 v54, v55
	ds_write_b16_d16_hi v54, v55 offset:144
	ds_write_b16 v54, v69 offset:288
	ds_write_b16_d16_hi v54, v69 offset:432
	ds_write_b16 v41, v70
	ds_write_b16_d16_hi v41, v70 offset:144
	ds_write_b16 v41, v71 offset:288
	ds_write_b16_d16_hi v41, v71 offset:432
	s_cbranch_scc1 .LBB0_197
	s_mov_b64 s[30:31], s[94:95]
	v_exp_f32_e32 v64, v48
	v_exp_f32_e32 v65, v49
	v_exp_f32_e32 v66, v46
	v_exp_f32_e32 v67, v47
	s_waitcnt lgkmcnt(0)
	s_add_u32 s30, s30, s22
	v_ashrrev_i32_e32 v147, 31, v146
	s_addc_u32 s31, s31, s23
	v_lshl_add_u64 v[46:47], v[146:147], 2, s[30:31]
	global_store_dwordx4 v[46:47], v[64:67], off

; __device__ __forceinline__ unsigned xb_add(unsigned* p, unsigned v) { return __hip_atomic_fetch_add(p, v, __ATOMIC_RELAXED, __HIP_MEMORY_SCOPE_AGENT); }
; #define P() (*(const Params*)(cp = cp_launder(cp)))
; __device__ __forceinline__ void xcd_barrier(XcdBarrier& b) {
;     asm volatile("s_waitcnt vmcnt(0)" ::: "memory");
;     __syncthreads();
;     if (threadIdx.x == 0) {
;         unsigned* bar = b.bar;
;         __builtin_amdgcn_s_waitcnt(0);
;         if (b.nloc == 0u) xcd_barrier_complete(bar, b.x, b.nloc, b.nx);
;         const unsigned nloc = b.nloc, nx = b.nx;
;         const unsigned old = xb_add(&bar[XB_XSUB(b.x)], 1u);
;         const unsigned gen = old / nloc;
;         if (old + 1u == (gen + 1u) * nloc) {
; __global__ __launch_bounds__(512, 2) void k_mega(Params p) {
;     ...
;     phase_prep(P(), shm); xcd_barrier(xb);
.LBB0_280:
	s_waitcnt vmcnt(0)
	s_waitcnt lgkmcnt(0)
	s_cmp_lg_u32 s77, 1
	s_cbranch_scc1 .Lprep_xb3
	v_readlane_b32 s40, v244, 6
	v_readlane_b32 s41, v244, 7
	s_nop 3
	s_branch .LBB0_96
